# P12 final-scan y_a stores write-through (sc1) so the P12->P13 barrier's L2 writeback has nothing left to flush
# speedup vs baseline: 1.0063x; 1.0016x over previous
.LBB0_1568:
	v_add_co_u32_e32 v8, vcc, 0xf9ff9000, v6
	s_add_i32 s0, s0, 16
	s_nop 0
	v_addc_co_u32_e32 v9, vcc, -1, v7, vcc
	v_add_co_u32_e32 v10, vcc, 0xfbff9000, v6
	s_cmp_lt_u32 s0, 48
	s_nop 0
	v_addc_co_u32_e32 v11, vcc, -1, v7, vcc
	v_add_co_u32_e32 v14, vcc, 0xf9ffa000, v6
	s_nop 1
	v_addc_co_u32_e32 v15, vcc, -1, v7, vcc
	v_add_co_u32_e32 v16, vcc, 0xfbffa000, v6
	s_nop 1
	v_addc_co_u32_e32 v17, vcc, -1, v7, vcc
	global_load_dword v3, v[8:9], off offset:-2048
	global_load_dword v18, v[10:11], off offset:-2048
	global_load_dword v19, v[10:11], off
	global_load_dword v21, v[14:15], off offset:-2048
	global_load_dword v22, v[16:17], off offset:-2048
	global_load_dword v25, v[16:17], off
	global_load_dword v23, v[14:15], off
	global_load_dword v20, v[8:9], off
	v_add_co_u32_e32 v8, vcc, 0xf9ffb000, v6
	s_waitcnt vmcnt(2)
	v_lshlrev_b32_e32 v24, 16, v25
	v_addc_co_u32_e32 v9, vcc, -1, v7, vcc
	v_add_co_u32_e32 v10, vcc, 0xfbffb000, v6
	v_and_b32_e32 v25, 0xffff0000, v25
	s_nop 0
	v_addc_co_u32_e32 v11, vcc, -1, v7, vcc
	v_add_co_u32_e32 v14, vcc, 0xf9ffc000, v6
	s_nop 1
	v_addc_co_u32_e32 v15, vcc, -1, v7, vcc
	v_add_co_u32_e32 v16, vcc, 0xfbffc000, v6
	s_nop 1
	v_addc_co_u32_e32 v17, vcc, -1, v7, vcc
	global_load_dword v27, v[8:9], off offset:-2048
	global_load_dword v29, v[10:11], off offset:-2048
	global_load_dword v30, v[10:11], off
	global_load_dword v31, v[14:15], off offset:-2048
	global_load_dword v32, v[16:17], off offset:-2048
	global_load_dword v33, v[16:17], off
	global_load_dword v34, v[14:15], off
	global_load_dword v35, v[8:9], off
	v_add_co_u32_e32 v8, vcc, 0xf9ffd000, v6
	s_waitcnt vmcnt(6)
	v_lshlrev_b32_e32 v28, 16, v29
	v_addc_co_u32_e32 v9, vcc, -1, v7, vcc
	v_add_co_u32_e32 v10, vcc, 0xfbffd000, v6
	v_and_b32_e32 v29, 0xffff0000, v29
	s_nop 0
	v_addc_co_u32_e32 v11, vcc, -1, v7, vcc
	v_add_co_u32_e32 v14, vcc, 0xf9ffe000, v6
	s_nop 1
	v_addc_co_u32_e32 v15, vcc, -1, v7, vcc
	v_add_co_u32_e32 v16, vcc, 0xfbffe000, v6
	s_nop 1
	v_addc_co_u32_e32 v17, vcc, -1, v7, vcc
	global_load_dword v36, v[8:9], off offset:-2048
	global_load_dword v37, v[10:11], off offset:-2048
	global_load_dword v38, v[10:11], off
	global_load_dword v39, v[14:15], off offset:-2048
	global_load_dword v40, v[16:17], off offset:-2048
	global_load_dword v41, v[16:17], off
	global_load_dword v42, v[14:15], off
	global_load_dword v43, v[8:9], off
	v_add_co_u32_e32 v8, vcc, 0xf9fff000, v6
	s_nop 1
	v_addc_co_u32_e32 v9, vcc, -1, v7, vcc
	v_add_co_u32_e32 v10, vcc, 0xfbfff000, v6
	s_nop 1
	v_addc_co_u32_e32 v11, vcc, -1, v7, vcc
	v_add_co_u32_e32 v14, vcc, 0xfa000000, v6
	s_nop 1
	v_addc_co_u32_e32 v15, vcc, -1, v7, vcc
	v_add_co_u32_e32 v16, vcc, 0xfc000000, v6
	s_nop 1
	v_addc_co_u32_e32 v17, vcc, -1, v7, vcc
	global_load_dword v44, v[8:9], off offset:-2048
	global_load_dword v45, v[10:11], off offset:-2048
	global_load_dword v46, v[10:11], off
	global_load_dword v47, v[14:15], off offset:-2048
	global_load_dword v48, v[16:17], off offset:-2048
	global_load_dword v49, v[16:17], off
	global_load_dword v50, v[14:15], off
	global_load_dword v51, v[8:9], off
	v_lshlrev_b32_e32 v8, 16, v3
	v_and_b32_e32 v3, 0xffff0000, v3
	v_mul_f32_e32 v3, 0x3fb8aa3b, v3
	v_exp_f32_e32 v9, v3
	v_lshlrev_b32_e32 v3, 16, v20
	v_mul_f32_e32 v3, 0x3fb8aa3b, v3
	v_exp_f32_e32 v14, v3
	v_and_b32_e32 v3, 0xffff0000, v20
	v_mul_f32_e32 v3, 0x3fb8aa3b, v3
	v_exp_f32_e32 v15, v3
	v_lshlrev_b32_e32 v3, 16, v21
	v_mul_f32_e32 v3, 0x3fb8aa3b, v3
	v_lshlrev_b32_e32 v10, 16, v18
	v_and_b32_e32 v11, 0xffff0000, v18
	v_exp_f32_e32 v18, v3
	v_and_b32_e32 v3, 0xffff0000, v21
	v_mul_f32_e32 v3, 0x3fb8aa3b, v3
	v_lshlrev_b32_e32 v16, 16, v19
	v_and_b32_e32 v17, 0xffff0000, v19
	v_exp_f32_e32 v19, v3
	v_lshlrev_b32_e32 v3, 16, v23
	v_mul_f32_e32 v8, 0x3fb8aa3b, v8
	v_mul_f32_e32 v3, 0x3fb8aa3b, v3
	v_exp_f32_e32 v8, v8
	v_lshlrev_b32_e32 v20, 16, v22
	v_and_b32_e32 v21, 0xffff0000, v22
	v_exp_f32_e32 v22, v3
	v_and_b32_e32 v3, 0xffff0000, v23
	v_mul_f32_e32 v3, 0x3fb8aa3b, v3
	v_exp_f32_e32 v23, v3
	v_lshlrev_b32_e32 v3, 16, v27
	v_mul_f32_e32 v3, 0x3fb8aa3b, v3
	v_exp_f32_e32 v26, v3
	v_and_b32_e32 v3, 0xffff0000, v27
	v_pk_fma_f32 v[4:5], v[4:5], v[8:9], v[10:11]
	v_add_co_u32_e32 v8, vcc, s5, v6
	v_mul_f32_e32 v3, 0x3fb8aa3b, v3
	s_nop 0
	v_addc_co_u32_e32 v9, vcc, -1, v7, vcc
	v_exp_f32_e32 v27, v3
	v_cvt_pk_bf16_f32 v3, v4, v5
	global_store_dword v[8:9], v3, off offset:-2048 sc1
	v_add_co_u32_e32 v8, vcc, s6, v6
	v_pk_fma_f32 v[4:5], v[4:5], v[14:15], v[16:17]
	s_nop 0
	v_addc_co_u32_e32 v9, vcc, -1, v7, vcc
	v_cvt_pk_bf16_f32 v3, v4, v5
	global_store_dword v[8:9], v3, off offset:-4096 sc1
	v_pk_fma_f32 v[4:5], v[4:5], v[18:19], v[20:21]
	s_waitcnt vmcnt(23)
	v_lshlrev_b32_e32 v10, 16, v30
	v_cvt_pk_bf16_f32 v3, v4, v5
	global_store_dword v[8:9], v3, off offset:-2048 sc1
	v_pk_fma_f32 v[4:5], v[4:5], v[22:23], v[24:25]
	v_and_b32_e32 v11, 0xffff0000, v30
	v_cvt_pk_bf16_f32 v3, v4, v5
	global_store_dword v[8:9], v3, off sc1
	v_add_co_u32_e32 v8, vcc, s7, v6
	v_pk_fma_f32 v[4:5], v[4:5], v[26:27], v[28:29]
	s_nop 0
	v_addc_co_u32_e32 v9, vcc, -1, v7, vcc
	v_cvt_pk_bf16_f32 v3, v4, v5
	global_store_dword v[8:9], v3, off offset:-2048 sc1
	s_waitcnt vmcnt(21)
	v_lshlrev_b32_e32 v3, 16, v35
	v_mul_f32_e32 v3, 0x3fb8aa3b, v3
	v_exp_f32_e32 v8, v3
	v_and_b32_e32 v3, 0xffff0000, v35
	v_mul_f32_e32 v3, 0x3fb8aa3b, v3
	v_exp_f32_e32 v9, v3
	v_lshlrev_b32_e32 v3, 16, v31
	v_mul_f32_e32 v3, 0x3fb8aa3b, v3
	v_exp_f32_e32 v14, v3
	v_and_b32_e32 v3, 0xffff0000, v31
	v_mul_f32_e32 v3, 0x3fb8aa3b, v3
	v_exp_f32_e32 v15, v3
	v_lshlrev_b32_e32 v3, 16, v34
	v_mul_f32_e32 v3, 0x3fb8aa3b, v3
	v_exp_f32_e32 v18, v3
	v_and_b32_e32 v3, 0xffff0000, v34
	v_mul_f32_e32 v3, 0x3fb8aa3b, v3
	v_exp_f32_e32 v19, v3
	s_waitcnt vmcnt(20)
	v_lshlrev_b32_e32 v3, 16, v36
	v_mul_f32_e32 v3, 0x3fb8aa3b, v3
	v_exp_f32_e32 v22, v3
	v_and_b32_e32 v3, 0xffff0000, v36
	v_mul_f32_e32 v3, 0x3fb8aa3b, v3
	v_exp_f32_e32 v23, v3
	s_waitcnt vmcnt(13)
	v_lshlrev_b32_e32 v3, 16, v43
	v_mul_f32_e32 v3, 0x3fb8aa3b, v3
	v_exp_f32_e32 v26, v3
	v_and_b32_e32 v3, 0xffff0000, v43
	v_mul_f32_e32 v3, 0x3fb8aa3b, v3
	v_exp_f32_e32 v27, v3
	v_lshlrev_b32_e32 v3, 16, v39
	v_mul_f32_e32 v3, 0x3fb8aa3b, v3
	v_exp_f32_e32 v30, v3
	v_and_b32_e32 v3, 0xffff0000, v39
	v_mul_f32_e32 v3, 0x3fb8aa3b, v3
	v_pk_fma_f32 v[4:5], v[4:5], v[8:9], v[10:11]
	v_add_co_u32_e32 v8, vcc, s8, v6
	v_lshlrev_b32_e32 v16, 16, v32
	v_and_b32_e32 v17, 0xffff0000, v32
	v_exp_f32_e32 v31, v3
	v_cvt_pk_bf16_f32 v3, v4, v5
	v_addc_co_u32_e32 v9, vcc, -1, v7, vcc
	v_lshlrev_b32_e32 v20, 16, v33
	v_and_b32_e32 v21, 0xffff0000, v33
	global_store_dword v[8:9], v3, off offset:-4096 sc1
	v_pk_fma_f32 v[4:5], v[4:5], v[14:15], v[16:17]
	v_lshlrev_b32_e32 v24, 16, v37
	v_cvt_pk_bf16_f32 v3, v4, v5
	global_store_dword v[8:9], v3, off offset:-2048 sc1
	v_pk_fma_f32 v[4:5], v[4:5], v[18:19], v[20:21]
	v_and_b32_e32 v25, 0xffff0000, v37
	v_cvt_pk_bf16_f32 v3, v4, v5
	global_store_dword v[8:9], v3, off sc1
	v_add_co_u32_e32 v8, vcc, s9, v6
	v_lshlrev_b32_e32 v28, 16, v38
	s_nop 0
	v_addc_co_u32_e32 v9, vcc, -1, v7, vcc
	v_and_b32_e32 v29, 0xffff0000, v38
	v_pk_fma_f32 v[4:5], v[4:5], v[22:23], v[24:25]
	v_lshlrev_b32_e32 v32, 16, v40
	v_cvt_pk_bf16_f32 v3, v4, v5
	global_store_dword v[8:9], v3, off offset:-2048 sc1
	v_add_co_u32_e32 v8, vcc, s24, v6
	v_pk_fma_f32 v[4:5], v[4:5], v[26:27], v[28:29]
	s_nop 0
	v_addc_co_u32_e32 v9, vcc, -1, v7, vcc
	v_cvt_pk_bf16_f32 v3, v4, v5
	global_store_dword v[8:9], v3, off offset:-4096 sc1
	v_lshlrev_b32_e32 v3, 16, v42
	v_mul_f32_e32 v3, 0x3fb8aa3b, v3
	v_exp_f32_e32 v10, v3
	v_and_b32_e32 v3, 0xffff0000, v42
	v_mul_f32_e32 v3, 0x3fb8aa3b, v3
	v_exp_f32_e32 v11, v3
	s_waitcnt vmcnt(17)
	v_lshlrev_b32_e32 v3, 16, v44
	v_mul_f32_e32 v3, 0x3fb8aa3b, v3
	v_exp_f32_e32 v16, v3
	v_and_b32_e32 v3, 0xffff0000, v44
	v_mul_f32_e32 v3, 0x3fb8aa3b, v3
	v_exp_f32_e32 v17, v3
	s_waitcnt vmcnt(10)
	v_lshlrev_b32_e32 v3, 16, v51
	v_mul_f32_e32 v3, 0x3fb8aa3b, v3
	v_exp_f32_e32 v20, v3
	v_and_b32_e32 v3, 0xffff0000, v51
	v_mul_f32_e32 v3, 0x3fb8aa3b, v3
	v_exp_f32_e32 v21, v3
	v_lshlrev_b32_e32 v3, 16, v47
	v_mul_f32_e32 v3, 0x3fb8aa3b, v3
	v_exp_f32_e32 v24, v3
	v_and_b32_e32 v3, 0xffff0000, v47
	v_mul_f32_e32 v3, 0x3fb8aa3b, v3
	v_exp_f32_e32 v25, v3
	v_lshlrev_b32_e32 v3, 16, v50
	v_mul_f32_e32 v3, 0x3fb8aa3b, v3
	v_exp_f32_e32 v28, v3
	v_and_b32_e32 v3, 0xffff0000, v50
	v_and_b32_e32 v33, 0xffff0000, v40
	v_mul_f32_e32 v3, 0x3fb8aa3b, v3
	v_lshlrev_b32_e32 v14, 16, v41
	v_and_b32_e32 v15, 0xffff0000, v41
	v_exp_f32_e32 v29, v3
	v_pk_fma_f32 v[4:5], v[4:5], v[30:31], v[32:33]
	v_lshlrev_b32_e32 v18, 16, v45
	v_cvt_pk_bf16_f32 v3, v4, v5
	v_and_b32_e32 v19, 0xffff0000, v45
	global_store_dword v[8:9], v3, off offset:-2048 sc1
	v_pk_fma_f32 v[4:5], v[4:5], v[10:11], v[14:15]
	v_lshlrev_b32_e32 v22, 16, v46
	v_cvt_pk_bf16_f32 v3, v4, v5
	global_store_dword v[8:9], v3, off sc1
	v_add_co_u32_e32 v8, vcc, s4, v6
	v_and_b32_e32 v23, 0xffff0000, v46
	v_pk_fma_f32 v[4:5], v[4:5], v[16:17], v[18:19]
	v_addc_co_u32_e32 v9, vcc, -1, v7, vcc
	v_cvt_pk_bf16_f32 v3, v4, v5
	v_lshlrev_b32_e32 v26, 16, v48
	v_and_b32_e32 v27, 0xffff0000, v48
	global_store_dword v[8:9], v3, off offset:-2048 sc1
	v_pk_fma_f32 v[4:5], v[4:5], v[20:21], v[22:23]
	v_lshlrev_b32_e32 v34, 16, v49
	v_cvt_pk_bf16_f32 v3, v4, v5
	v_and_b32_e32 v35, 0xffff0000, v49
	global_store_dword v[6:7], v3, off offset:-4096 sc1
	v_pk_fma_f32 v[4:5], v[4:5], v[24:25], v[26:27]
	s_nop 0
	v_cvt_pk_bf16_f32 v3, v4, v5
	global_store_dword v[6:7], v3, off offset:-2048 sc1
	v_pk_fma_f32 v[4:5], v[4:5], v[28:29], v[34:35]
	s_nop 0
	v_cvt_pk_bf16_f32 v3, v4, v5
	global_store_dword v[6:7], v3, off sc1
	v_lshl_add_u64 v[6:7], v[6:7], 0, s[22:23]
	s_cbranch_scc1 .LBB0_1568
	v_add_u32_e32 v12, s34, v12
	v_cmp_lt_i32_e32 vcc, s25, v12
	s_or_b64 s[12:13], vcc, s[12:13]
	v_add_u32_e32 v13, s3, v13
	s_andn2_b64 exec, exec, s[12:13]
	s_cbranch_execnz .LBB0_1557
